# layer-0 OUT/GU2/D2/PG/PE weight conversions moved out of the prologue into the idle waves 4-7 of layer 0's attention phase (prologue 160 -> 67 us, attention phase longer)
# speedup vs baseline: 1.0083x; 1.0083x over previous
; __device__ __forceinline__ void prologue(ArgsP a, const Ctx& c) {
;     ...
;     constexpr int N_MID = DEFER_PG0 - DEFER_LO, N_PRO = PER_LAYER + N_MID + (PER_LAYER - DEFER_PG1);
;     for (int j = c.gw; j < N_PRO; j += c.NGW) {
;         const int it = j < PER_LAYER ? j : (j < PER_LAYER + N_MID ? PER_LAYER + DEFER_LO + (j - PER_LAYER) : PER_LAYER + DEFER_PG1 + (j - PER_LAYER - N_MID));
;         convert_item(a, c, it, scr);
; __device__ __forceinline__ void attn_phase(const Ctx& c, ArgsP a, int l, int ctr_slot) {
;     unsigned* ctr0 = (unsigned*)(c.ws + WS_CTL) + 64 * ctr_slot;
;     const int myq = (int)(__builtin_amdgcn_s_getreg((3 << 11) | 20) & 7u);
;     for (int qi = 0; qi < 8; ++qi) {
;         const int q = (myq + qi) & 7;
;         unsigned* ctr = ctr0 + 64 * q;
;         for (;;) {
;             int t = 0;
;             if (c.lane == 0) t = (int)atomicAdd(ctr, 1u);
;             t = __builtin_amdgcn_readfirstlane(t);
;             if (t >= 448) break;
;             Ctx ct = c; { int ln = c.lane; asm volatile("" : "+v"(ln)); ct.lane = ln; }
;             int ll = l; asm volatile("" : "+s"(ll));
;             if (t >= 384) { const int f = (t - 384) * 8 + q; gla_final_task(ct, a, ll, f >> 5, f & 31); continue; }
;             const int grp = t / 192, u = t % 192, qt = 63 - u / 3, j = grp * 3 + u % 3, hh48 = j * 8 + q;
;             if (hh48 < 24) diff_task(ct, a, ll, hh48, qt); else moba_task(ct, hh48 - 24, qt);
;         }
;     }
; }
.Lattn_hi:
	v_readlane_b32 s2, v254, 53
	s_nop 3
	s_cmp_lg_u32 s2, 0
	s_cbranch_scc1 .LBB0_219
	s_mov_b32 s32, 1
	v_readlane_b32 s0, v254, 13
	v_readlane_b32 s1, v254, 14
	s_nop 4
	s_movk_i32 s46, 0x5800
	s_movk_i32 s65, 0x78
	s_movk_i32 s70, 0x9200
	s_movk_i32 s75, 0x6040
	s_mov_b32 s92, 0x2c00000
	s_lshl_b32 s14, s76, 2
	s_add_i32 s14, s14, s4
	s_add_i32 s14, s14, -4
	v_lshlrev_b32_e32 v2, 3, v198
	v_readlane_b32 s2, v254, 62
	s_lshl_b32 s2, s2, 14
	v_lshrrev_b32_e32 v3, 5, v198
	v_and_b32_e32 v4, 31, v228
	s_add_i32 s2, s2, 0
	v_lshlrev_b32_e32 v0, 2, v4
	v_mul_u32_u24_e32 v5, 0x84, v3
	v_lshrrev_b32_e32 v7, 3, v198
	v_and_b32_e32 v6, 56, v2
	s_add_u32 s12, s48, 0x100000
	v_add3_u32 v5, s2, v0, v5
	v_mul_u32_u24_e32 v0, 0x84, v6
	v_lshlrev_b32_e32 v8, 2, v7
	s_addc_u32 s13, s49, 0
	v_add3_u32 v8, s2, v0, v8
	v_or_b32_e32 v9, 8, v7
	v_or_b32_e32 v10, 16, v7
	v_or_b32_e32 v11, 24, v7
	s_branch .LBB0_543

; __device__ __forceinline__ void prologue(ArgsP a, const Ctx& c) {
;     ...
;     constexpr int N_MID = DEFER_PG0 - DEFER_LO, N_PRO = PER_LAYER + N_MID + (PER_LAYER - DEFER_PG1);
;     for (int j = c.gw; j < N_PRO; j += c.NGW) {
;         const int it = j < PER_LAYER ? j : (j < PER_LAYER + N_MID ? PER_LAYER + DEFER_LO + (j - PER_LAYER) : PER_LAYER + DEFER_PG1 + (j - PER_LAYER - N_MID));
;         convert_item(a, c, it, scr);
;     }
.LBB0_540:
	s_mov_b32 s32, 0
	s_cmp_gt_i32 s66, 0xbdff
	v_lshlrev_b32_e32 v2, 3, v198
	s_cbranch_scc1 .LBB0_598
	v_readlane_b32 s2, v254, 62
	s_lshl_b32 s2, s2, 14
	v_lshrrev_b32_e32 v3, 5, v198
	v_and_b32_e32 v4, 31, v228
	s_add_i32 s2, s2, 0
	v_lshlrev_b32_e32 v0, 2, v4
	v_mul_u32_u24_e32 v5, 0x84, v3
	v_lshrrev_b32_e32 v7, 3, v198
	v_and_b32_e32 v6, 56, v2
	s_add_u32 s12, s48, 0x100000
	v_add3_u32 v5, s2, v0, v5
	v_mul_u32_u24_e32 v0, 0x84, v6
	v_lshlrev_b32_e32 v8, 2, v7
	s_addc_u32 s13, s49, 0
	v_add3_u32 v8, s2, v0, v8
	v_or_b32_e32 v9, 8, v7
	v_or_b32_e32 v10, 16, v7
	v_or_b32_e32 v11, 24, v7
	s_mov_b32 s14, s66
	s_branch .LBB0_543
.LBB0_542:
	s_cmp_lg_u32 s32, 0
	s_cselect_b32 s3, 1, 0
	s_lshr_b32 s3, s62, s3
	s_add_i32 s14, s14, s3
	s_movk_i32 s2, 0x6aff
	s_cmp_lg_u32 s32, 0
	s_cselect_b32 s2, 0x52ff, s2
	s_cmp_gt_i32 s14, s2
	s_cbranch_scc1 .Lconv_exit
.LBB0_543:
	s_cmp_lg_u32 s32, 0
	s_cbranch_scc1 .Lmap_def
	s_mov_b32 s10, s14
	s_cmpk_lt_i32 s14, 0x2c00
	s_cbranch_scc1 .LBB0_548
	s_add_i32 s10, s14, 0x2c00
	s_cmpk_lt_i32 s14, 0x4200
	s_cbranch_scc1 .LBB0_548
	s_add_i32 s10, s14, 0x4200
	s_cmpk_lt_i32 s14, 0x5a00
	s_cbranch_scc1 .LBB0_548
	s_add_i32 s10, s14, 0xe700
	s_cmpk_lt_i32 s14, 0x6a00
	s_cbranch_scc1 .LBB0_548
	s_add_i32 s10, s14, 0xef00
	s_branch .LBB0_548
.Lmap_def:
	s_add_i32 s10, s14, 0x2c00
	s_cmpk_lt_i32 s14, 0x2c00
	s_cbranch_scc1 .LBB0_548
	s_add_i32 s10, s14, 0x4200
	s_cmpk_lt_i32 s14, 0x4200
	s_cbranch_scc1 .LBB0_548
	s_add_i32 s10, s14, 0x5a00

; __device__ __forceinline__ void prologue(ArgsP a, const Ctx& c) {
;     ...
;     for (int j = c.gw; j < N_PRO; j += c.NGW) {
;         const int it = j < PER_LAYER ? j : (j < PER_LAYER + N_MID ? PER_LAYER + DEFER_LO + (j - PER_LAYER) : PER_LAYER + DEFER_PG1 + (j - PER_LAYER - N_MID));
;         convert_item(a, c, it, scr);
;     }
; __device__ __forceinline__ void attn_phase(const Ctx& c, ArgsP a, int l, int ctr_slot) {
;     unsigned* ctr0 = (unsigned*)(c.ws + WS_CTL) + 64 * ctr_slot;
;     const int myq = (int)(__builtin_amdgcn_s_getreg((3 << 11) | 20) & 7u);
;     for (int qi = 0; qi < 8; ++qi) {
.Lconv_exit:
	s_cmp_lg_u32 s32, 0
	s_cbranch_scc0 .LBB0_598
	s_mov_b32 s32, 0
	s_waitcnt vmcnt(0) lgkmcnt(0)
	s_branch .LBB0_219
